# grid barrier followers: L1-only invalidate (buffer_inv sc0); the XCD leader's agent-scope invalidate covers the shared L2 before it releases them
# speedup vs baseline: 1.0156x; 1.0142x over previous
; __device__ __forceinline__ unsigned xb_ld(unsigned* p)              { return __hip_atomic_load(p, __ATOMIC_RELAXED, __HIP_MEMORY_SCOPE_AGENT); }
; #define XB_SPIN(cond, bar) do { unsigned _sp = 0; while (cond) { __builtin_amdgcn_s_sleep(1); \
;     if ((++_sp & 255u) == 0u) { if (xb_ld(&(bar)[XB_TMO])) break; if (_sp > XB_SPIN_CAP) { atomicAdd(&(bar)[XB_TMO], 1u); break; } } } } while (0)
; __device__ __forceinline__ void xcd_barrier(unsigned* bar, volatile LAS unsigned* st, const int tid) {
;     ...
;             XB_SPIN(xb_ld(&bar[XB_XGEN(x)]) == gen, bar);
;             __builtin_amdgcn_fence(__ATOMIC_ACQUIRE, "agent");
;             asm volatile("s_waitcnt vmcnt(0)" ::: "memory");
.LBB0_81:
	s_or_b64 exec, exec, s[30:31]
	s_waitcnt vmcnt(0) lgkmcnt(0)
	buffer_inv sc0
	s_waitcnt vmcnt(0)
